# v21 plus kk normalisation via v_rsq+v_min (one transcendental instead of sqrt+rcp) and exp(-x) taken from the same scaled argument with a source negation modifier
# speedup vs baseline: 1.0164x; 1.0083x over previous
.LBB0_698:
	v_cndmask_b32_e64 v29, v34, 0, s[24:25]
	v_readlane_b32 s80, v233, 39
	v_add_f32_e32 v34, v35, v29
	v_readlane_b32 s81, v233, 40
	v_readlane_b32 s0, v233, 41
	v_readlane_b32 s1, v233, 42
	v_cndmask_b32_e64 v29, v29, v34, s[80:81]
	v_add_f32_e32 v32, v32, v29
	v_cndmask_b32_e64 v29, v29, v32, s[0:1]
	v_readlane_b32 s0, v233, 43
	v_add_f32_e32 v32, v33, v29
	v_readlane_b32 s1, v233, 44
	s_nop 1
	v_cndmask_b32_e64 v29, v29, v32, s[0:1]
	v_readlane_b32 s0, v233, 45
	v_add_f32_e32 v30, v30, v29
	v_readlane_b32 s1, v233, 46
	s_nop 0
	s_nop 0
	v_cndmask_b32_e64 v29, v29, v30, s[0:1]
	v_readlane_b32 s0, v233, 47
	v_add_f32_e32 v31, v31, v29
	v_readlane_b32 s1, v233, 48
	s_nop 1
	v_cndmask_b32_e64 v29, v29, v31, s[0:1]
	v_add_f32_e32 v18, v18, v29
	s_nop 1
	s_nop 0
	v_readlane_b32 s0, v233, 49
	v_readlane_b32 s1, v233, 50
	s_nop 1
	v_cndmask_b32_e64 v18, v29, v18, s[0:1]
	v_readlane_b32 s0, v233, 51
	v_add_f32_e32 v19, v19, v18
	v_readlane_b32 s1, v233, 52
	s_nop 1
	v_cndmask_b32_e64 v18, v18, v19, s[0:1]
	v_rsq_f32_e32 v19, s46
	s_nop 0
	v_min_f32_e32 v19, 0x5368d4a5, v19
	s_nop 0
	v_mul_f32_e32 v19, v112, v19
	v_add_f32_e32 v109, v109, v18
	v_mul_f32_e32 v17, v19, v17
	v_rsq_f32_e32 v29, s19
	s_nop 0
	v_min_f32_e32 v29, 0x5368d4a5, v29
	s_nop 0
	v_mul_f32_e32 v29, v111, v29
	v_mul_f32_e32 v15, v29, v15
	s_nop 0
	v_rsq_f32_e32 v30, s18
	s_nop 0
	v_min_f32_e32 v30, 0x5368d4a5, v30
	s_nop 0
	v_mul_f32_e32 v114, v110, v30
	v_mul_f32_e32 v16, v114, v16
	s_nop 0
	v_rsq_f32_e32 v30, s17
	s_nop 0
	v_min_f32_e32 v30, 0x5368d4a5, v30
	s_nop 0
	v_mul_f32_e32 v104, v104, v30
	v_mul_f32_e32 v14, v104, v14
	s_nop 0
	v_rsq_f32_e32 v30, s9
	s_nop 0
	v_min_f32_e32 v30, 0x5368d4a5, v30
	s_nop 0
	v_mul_f32_e32 v100, v100, v30
	v_mul_f32_e32 v13, v100, v13
	s_nop 0
	v_rsq_f32_e32 v30, s8
	s_nop 0
	v_min_f32_e32 v30, 0x5368d4a5, v30
	s_nop 0
	v_mul_f32_e32 v115, v99, v30
	v_lshlrev_b32_e32 v110, 16, v61
	v_mul_f32_e32 v11, v115, v11
	s_nop 0
	v_and_b32_e32 v31, 0xffff0000, v88
	v_rsq_f32_e32 v30, s7
	s_nop 0
	v_min_f32_e32 v30, 0x5368d4a5, v30
	s_nop 0
	v_mul_f32_e32 v116, v98, v30
	v_lshlrev_b32_e32 v30, 16, v88
	v_lshlrev_b32_e32 v33, 16, v54
	v_lshlrev_b32_e32 v35, 16, v52
	v_lshlrev_b32_e32 v34, 16, v45
	v_mov_b32_e32 v32, v31
	v_pk_add_f32 v[30:31], v[30:31], v[34:35] neg_lo:[0,1] neg_hi:[0,1]
	v_pk_add_f32 v[98:99], v[34:35], v[32:33] neg_lo:[0,1] neg_hi:[0,1]
	v_pk_fma_f32 v[30:31], v[24:25], v[30:31], v[34:35] op_sel_hi:[0,1,1]
	v_pk_fma_f32 v[34:35], v[98:99], v[24:25], v[32:33] op_sel_hi:[1,0,1]
	v_lshlrev_b32_e32 v99, 16, v66
	v_lshlrev_b32_e32 v98, 16, v56
	v_lshlrev_b32_e32 v111, 16, v71
	v_pk_mov_b32 v[32:33], v[32:33], v[110:111] op_sel:[1,0]
	v_mul_f32_e32 v12, v116, v12
	v_pk_add_f32 v[32:33], v[32:33], v[98:99] neg_lo:[0,1] neg_hi:[0,1]
	v_pk_fma_f32 v[32:33], v[32:33], v[24:25], v[98:99] op_sel_hi:[1,0,1]
	s_nop 0
	s_nop 1
	v_pk_add_f32 v[112:113], v[98:99], v[110:111] neg_lo:[0,1] neg_hi:[0,1]
	s_nop 0
	v_pk_fma_f32 v[98:99], v[112:113], v[24:25], v[110:111] op_sel_hi:[1,0,1]
	v_rsq_f32_e32 v110, s6
	s_nop 0
	v_min_f32_e32 v110, 0x5368d4a5, v110
	s_nop 0
	v_mul_f32_e32 v97, v97, v110
	v_mul_f32_e32 v110, 0x3fb8aa3b, v18
	v_exp_f32_e32 v111, v110
	v_mul_f32_e32 v110, 0x3fb8aa3b, v109
	v_exp_f32_e32 v112, v110
	v_exp_f32_e64 v110, -v110
	v_mul_f32_e32 v10, v97, v10
	v_mul_f32_e64 v97, v111, -v97
	v_mul_f32_e32 v96, v96, v112
	v_cvt_pk_bf16_f32 v109, v97, s0
	v_cvt_pk_bf16_f32 v96, v96, s0
	v_mul_f32_e32 v97, v10, v110
	v_mul_f32_e32 v111, v0, v110
	v_cvt_pk_bf16_f32 v113, v30, v31
	v_add_f32_e32 v31, v108, v18
	v_cvt_pk_bf16_f32 v97, v97, s0
	v_cvt_pk_bf16_f32 v111, v111, s0
	ds_write_b16 v204, v109
	ds_write_b16 v204, v96 offset:9216
	ds_write_b16 v204, v97 offset:18432
	ds_write_b16 v204, v111 offset:27648
	v_mul_f32_e32 v96, 0x3fb8aa3b, v31
	v_exp_f32_e32 v97, v96
	v_exp_f32_e64 v96, -v96
	v_mul_f32_e64 v31, v112, -v116
	v_cvt_pk_bf16_f32 v112, v34, v35
	v_add_f32_e32 v34, v107, v18
	v_mul_f32_e32 v111, v4, v96
	v_mul_f32_e32 v35, 0x3fb8aa3b, v34
	v_cvt_pk_bf16_f32 v31, v31, s0
	v_mul_f32_e32 v94, v94, v97
	v_mul_f32_e32 v108, v12, v96
	v_cvt_pk_bf16_f32 v111, v111, s0
	v_exp_f32_e32 v35, v35
	v_mul_f32_e32 v34, 0xbfb8aa3b, v34
	v_cvt_pk_bf16_f32 v94, v94, s0
	v_cvt_pk_bf16_f32 v108, v108, s0
	ds_write_b16 v204, v31 offset:144
	ds_write_b16 v204, v94 offset:9360
	ds_write_b16 v204, v108 offset:18576
	ds_write_b16 v204, v111 offset:27792
	v_exp_f32_e32 v111, v34
	v_mul_f32_e64 v34, v97, -v115
	v_cvt_pk_bf16_f32 v94, v34, s0
	v_mul_f32_e32 v34, v92, v35
	v_cvt_pk_bf16_f32 v34, v34, s0
	v_mul_f32_e32 v92, v11, v111
	v_mul_f32_e32 v97, v1, v111
	v_cvt_pk_bf16_f32 v92, v92, s0
	v_cvt_pk_bf16_f32 v97, v97, s0
	ds_write_b16 v204, v94 offset:288
	ds_write_b16 v204, v34 offset:9504
	ds_write_b16 v204, v92 offset:18720
	ds_write_b16 v204, v97 offset:27936
	v_add_f32_e32 v34, v106, v18
	v_mul_f32_e32 v92, 0x3fb8aa3b, v34
	v_exp_f32_e64 v97, -v92
	v_exp_f32_e32 v92, v92
	v_mul_f32_e64 v34, v35, -v100
	v_cvt_pk_bf16_f32 v100, v34, s0
	v_mul_f32_e32 v34, v90, v92
	v_cvt_pk_bf16_f32 v34, v34, s0
	v_mul_f32_e32 v35, v13, v97
	v_mul_f32_e32 v90, v5, v97
	v_cvt_pk_bf16_f32 v35, v35, s0
	v_cvt_pk_bf16_f32 v90, v90, s0
	ds_write_b16 v204, v100 offset:432
	ds_write_b16 v204, v34 offset:9648
	ds_write_b16 v204, v35 offset:18864
	ds_write_b16 v204, v90 offset:28080
	v_add_f32_e32 v34, v105, v18
	v_mul_f32_e32 v35, 0x3fb8aa3b, v34
	v_exp_f32_e64 v34, -v35
	v_exp_f32_e32 v35, v35
	v_mul_f32_e64 v90, v92, -v104
	v_cvt_pk_bf16_f32 v105, v32, v33
	v_add_f32_e32 v32, v103, v18
	v_cvt_pk_bf16_f32 v92, v90, s0
	v_mul_f32_e32 v90, v95, v35
	v_mul_f32_e32 v33, 0x3fb8aa3b, v32
	v_cvt_pk_bf16_f32 v90, v90, s0
	v_mul_f32_e32 v95, v14, v34
	v_mul_f32_e32 v104, v6, v34
	v_exp_f32_e32 v33, v33
	v_mul_f32_e32 v32, 0xbfb8aa3b, v32
	v_cvt_pk_bf16_f32 v95, v95, s0
	v_cvt_pk_bf16_f32 v104, v104, s0
	ds_write_b16 v204, v92 offset:576
	ds_write_b16 v204, v90 offset:9792
	ds_write_b16 v204, v95 offset:19008
	ds_write_b16 v204, v104 offset:28224
	v_exp_f32_e32 v90, v32
	v_mul_f32_e64 v32, v35, -v114
	v_mul_f32_e32 v35, v93, v33
	v_cvt_pk_bf16_f32 v32, v32, s0
	v_cvt_pk_bf16_f32 v35, v35, s0
	v_mul_f32_e32 v93, v16, v90
	v_mul_f32_e32 v95, v8, v90
	v_cvt_pk_bf16_f32 v93, v93, s0
	v_cvt_pk_bf16_f32 v95, v95, s0
	ds_write_b16 v204, v32 offset:720
	ds_write_b16 v204, v35 offset:9936
	ds_write_b16 v204, v93 offset:19152
	ds_write_b16 v204, v95 offset:28368
	v_add_f32_e32 v35, v102, v18
	v_mul_f32_e32 v93, 0x3fb8aa3b, v35
	v_exp_f32_e64 v35, -v93
	v_exp_f32_e32 v93, v93
	v_mul_f32_e64 v29, v33, -v29
	v_mul_f32_e32 v33, v91, v93
	v_cvt_pk_bf16_f32 v29, v29, s0
	v_cvt_pk_bf16_f32 v33, v33, s0
	v_mul_f32_e32 v91, v15, v35
	v_mul_f32_e32 v95, v7, v35
	v_add_f32_e32 v18, v101, v18
	v_cvt_pk_bf16_f32 v91, v91, s0
	v_cvt_pk_bf16_f32 v95, v95, s0
	ds_write_b16 v204, v29 offset:864
	ds_write_b16 v204, v33 offset:10080
	ds_write_b16 v204, v91 offset:19296
	ds_write_b16 v204, v95 offset:28512
	v_mul_f32_e32 v33, 0x3fb8aa3b, v18
	v_exp_f32_e64 v91, -v33
	v_exp_f32_e32 v33, v33
	v_mul_f32_e64 v18, v93, -v19
	v_mul_f32_e32 v19, v89, v33
	v_cvt_pk_bf16_f32 v18, v18, s0
	v_cvt_pk_bf16_f32 v19, v19, s0
	v_mul_f32_e32 v33, v17, v91
	v_mul_f32_e32 v89, v9, v91
	v_cvt_pk_bf16_f32 v33, v33, s0
	v_cvt_pk_bf16_f32 v89, v89, s0
	ds_write_b16 v204, v18 offset:1008
	ds_write_b16 v204, v19 offset:10224
	ds_write_b16 v204, v33 offset:19440
	ds_write_b16 v204, v89 offset:28656
	v_perm_b32 v30, v31, v109, s96
	v_perm_b32 v31, v100, v94, s96
	v_perm_b32 v33, v18, v29, s96
	v_perm_b32 v32, v32, v92, s96
	v_pk_mul_f32 v[18:19], v[2:3], v[110:111] op_sel_hi:[0,1]
	ds_write_b128 v159, v[30:33] offset:36864
	v_pk_mul_f32 v[30:31], v[2:3], v[96:97] op_sel_hi:[0,1]
	v_pk_mul_f32 v[10:11], v[10:11], v[18:19]
	v_pk_mul_f32 v[0:1], v[0:1], v[18:19]
	v_cvt_pk_bf16_f32 v32, v10, v11
	v_pk_mul_f32 v[10:11], v[12:13], v[30:31]
	v_cvt_pk_bf16_f32 v98, v98, v99
	v_cvt_pk_bf16_f32 v10, v10, v11
	v_perm_b32 v11, v10, v32, s97
	v_perm_b32 v10, v10, v32, s96
	v_pk_mul_f32 v[32:33], v[2:3], v[34:35] op_sel_hi:[0,1]
	v_pk_mul_f32 v[34:35], v[2:3], v[90:91] op_sel_hi:[0,1]
	v_pk_mul_f32 v[12:13], v[14:15], v[32:33]
	s_mov_b64 s[0:1], -1
	v_cvt_pk_bf16_f32 v2, v12, v13
	v_pk_mul_f32 v[12:13], v[16:17], v[34:35]
	s_and_b64 vcc, exec, s[80:81]
	v_cvt_pk_bf16_f32 v12, v12, v13
	v_perm_b32 v13, v12, v2, s97
	v_perm_b32 v12, v12, v2, s96
	v_cvt_pk_bf16_f32 v2, v0, v1
	v_pk_mul_f32 v[0:1], v[4:5], v[30:31]
	ds_write_b128 v159, v[10:13] offset:46080
	v_cvt_pk_bf16_f32 v0, v0, v1
	v_perm_b32 v5, v0, v2, s97
	v_perm_b32 v4, v0, v2, s96
	v_pk_mul_f32 v[0:1], v[6:7], v[32:33]
	v_mov_b32_e32 v12, s55
	v_cvt_pk_bf16_f32 v2, v0, v1
	v_pk_mul_f32 v[0:1], v[8:9], v[34:35]
	s_nop 0
	v_cvt_pk_bf16_f32 v0, v0, v1
	v_perm_b32 v7, v0, v2, s97
	v_perm_b32 v6, v0, v2, s96
	ds_write_b128 v159, v[4:7] offset:55296
	v_perm_b32 v5, v112, v113, s97
	v_perm_b32 v4, v112, v113, s96
	v_perm_b32 v7, v98, v105, s97
	v_perm_b32 v6, v98, v105, s96
	ds_write_b128 v159, v[4:7] offset:64512
	s_waitcnt lgkmcnt(0)
	s_barrier
	s_nop 0
	v_and_b32_e32 v0, 15, v28
	v_and_b32_e32 v1, -16, v28
	v_mad_u32_u24 v12, v0, s76, v12
	v_add_u32_e32 v30, v12, v1
	ds_read_b128 v[8:11], v140
	ds_read_b128 v[4:7], v140 offset:64
	ds_read_b128 v[16:19], v156
	ds_read_b128 v[12:15], v156 offset:64
	v_ashrrev_i32_e32 v2, 4, v28
	v_lshlrev_b32_e32 v29, 2, v2
	v_lshlrev_b32_e32 v2, 3, v2
	v_or_b32_e32 v89, v29, v69
	s_cbranch_vccz .LBB0_700
	s_waitcnt lgkmcnt(1)
	v_mfma_f32_16x16x32_bf16 v[94:97], v[16:19], v[8:11], 0
	s_mov_b64 s[0:1], 0
	s_waitcnt lgkmcnt(0)
	v_mfma_f32_16x16x32_bf16 v[94:97], v[12:15], v[4:7], v[94:97]
	s_nop 7
	v_bfi_b32 v35, v196, v94, v206
	v_and_b32_e32 v90, v166, v95
	v_cvt_pk_bf16_f32 v90, v35, v90
	v_and_b32_e32 v91, v199, v96
	v_and_b32_e32 v93, v202, v97
	v_cvt_pk_bf16_f32 v91, v91, v93
	ds_write_b64 v151, v[90:91]
